# 64-byte alignment of the GEMM K-loop heads and the attention loop head
# baseline (speedup 1.0000x reference)
.LBB0_255:
	s_ashr_i32 s13, s12, 31
	s_lshl_b64 s[18:19], s[12:13], 19
	s_add_u32 s18, s34, s18
	s_addc_u32 s19, s35, s19
	s_and_b64 s[20:21], s[16:17], exec
	s_cselect_b32 s13, s19, s27
	s_cselect_b32 s23, s18, s26
	s_ashr_i32 s15, s14, 31
	s_lshl_b64 s[20:21], s[14:15], 19
	s_add_u32 s20, s36, s20
	s_addc_u32 s21, s37, s21
	s_and_b64 s[30:31], s[16:17], exec
	s_cselect_b32 s15, s21, s29
	s_cselect_b32 s25, s20, s28
	s_add_u32 s26, s26, 0x40080
	s_addc_u32 s27, s27, 0
	s_add_u32 s60, s28, 0x100
	v_mov_b32_e32 v0, 0
	s_addc_u32 s61, s29, 0
	s_mov_b32 s70, -2
	s_waitcnt lgkmcnt(0)
	v_mov_b32_e32 v1, v0
	v_mov_b32_e32 v2, v0
	v_mov_b32_e32 v3, v0
	v_mov_b32_e32 v4, v0
	v_mov_b32_e32 v5, v0
	v_mov_b32_e32 v6, v0
	v_mov_b32_e32 v7, v0
	v_mov_b32_e32 v8, v0
	v_mov_b32_e32 v9, v0
	v_mov_b32_e32 v10, v0
	v_mov_b32_e32 v11, v0
	v_mov_b32_e32 v12, v0
	v_mov_b32_e32 v13, v0
	v_mov_b32_e32 v14, v0
	v_mov_b32_e32 v15, v0
	v_mov_b32_e32 v16, v0
	v_mov_b32_e32 v17, v0
	v_mov_b32_e32 v18, v0
	v_mov_b32_e32 v19, v0
	v_mov_b32_e32 v20, v0
	v_mov_b32_e32 v21, v0
	v_mov_b32_e32 v22, v0
	v_mov_b32_e32 v23, v0
	v_mov_b32_e32 v24, v0
	v_mov_b32_e32 v25, v0
	v_mov_b32_e32 v26, v0
	v_mov_b32_e32 v27, v0
	v_mov_b32_e32 v28, v0
	v_mov_b32_e32 v29, v0
	v_mov_b32_e32 v30, v0
	v_mov_b32_e32 v31, v0
	v_mov_b32_e32 v56, v0
	v_mov_b32_e32 v57, v0
	v_mov_b32_e32 v58, v0
	v_mov_b32_e32 v59, v0
	v_mov_b32_e32 v64, v0
	v_mov_b32_e32 v65, v0
	v_mov_b32_e32 v66, v0
	v_mov_b32_e32 v67, v0
	v_mov_b32_e32 v72, v0
	v_mov_b32_e32 v73, v0
	v_mov_b32_e32 v74, v0
	v_mov_b32_e32 v75, v0
	v_mov_b32_e32 v76, v0
	v_mov_b32_e32 v77, v0
	v_mov_b32_e32 v78, v0
	v_mov_b32_e32 v79, v0
	v_mov_b32_e32 v80, v0
	v_mov_b32_e32 v81, v0
	v_mov_b32_e32 v82, v0
	v_mov_b32_e32 v83, v0
	v_mov_b32_e32 v84, v0
	v_mov_b32_e32 v85, v0
	v_mov_b32_e32 v86, v0
	v_mov_b32_e32 v87, v0
	v_mov_b32_e32 v88, v0
	v_mov_b32_e32 v89, v0
	v_mov_b32_e32 v90, v0
	v_mov_b32_e32 v91, v0
	v_mov_b32_e32 v92, v0
	v_mov_b32_e32 v93, v0
	v_mov_b32_e32 v94, v0
	v_mov_b32_e32 v95, v0
	v_mov_b32_e32 v32, v0
	v_mov_b32_e32 v33, v0
	v_mov_b32_e32 v34, v0
	v_mov_b32_e32 v35, v0
	s_waitcnt lgkmcnt(0)
	v_mov_b32_e32 v36, v0
	v_mov_b32_e32 v37, v0
	v_mov_b32_e32 v38, v0
	v_mov_b32_e32 v39, v0
	v_mov_b32_e32 v40, v0
	v_mov_b32_e32 v41, v0
	v_mov_b32_e32 v42, v0
	v_mov_b32_e32 v43, v0
	v_mov_b32_e32 v44, v0
	v_mov_b32_e32 v45, v0
	v_mov_b32_e32 v46, v0
	v_mov_b32_e32 v47, v0
	v_mov_b32_e32 v48, v0
	v_mov_b32_e32 v49, v0
	v_mov_b32_e32 v50, v0
	v_mov_b32_e32 v51, v0
	v_mov_b32_e32 v52, v0
	v_mov_b32_e32 v53, v0
	v_mov_b32_e32 v54, v0
	v_mov_b32_e32 v55, v0
	v_mov_b32_e32 v60, v0
	v_mov_b32_e32 v61, v0
	v_mov_b32_e32 v62, v0
	v_mov_b32_e32 v63, v0
	v_mov_b32_e32 v68, v0
	v_mov_b32_e32 v69, v0
	v_mov_b32_e32 v70, v0
	v_mov_b32_e32 v71, v0
	v_mov_b32_e32 v96, v0
	v_mov_b32_e32 v97, v0
	v_mov_b32_e32 v98, v0
	v_mov_b32_e32 v99, v0
	v_mov_b32_e32 v100, v0
	v_mov_b32_e32 v101, v0
	v_mov_b32_e32 v102, v0
	v_mov_b32_e32 v103, v0
	v_mov_b32_e32 v104, v0
	v_mov_b32_e32 v105, v0
	v_mov_b32_e32 v106, v0
	v_mov_b32_e32 v107, v0
	v_mov_b32_e32 v108, v0
	v_mov_b32_e32 v109, v0
	v_mov_b32_e32 v110, v0
	v_mov_b32_e32 v111, v0
	v_mov_b32_e32 v112, v0
	v_mov_b32_e32 v113, v0
	v_mov_b32_e32 v114, v0
	v_mov_b32_e32 v115, v0
	v_mov_b32_e32 v116, v0
	v_mov_b32_e32 v117, v0
	v_mov_b32_e32 v118, v0
	v_mov_b32_e32 v119, v0
	v_mov_b32_e32 v120, v0
	v_mov_b32_e32 v121, v0
	v_mov_b32_e32 v122, v0
	v_mov_b32_e32 v123, v0
	v_mov_b32_e32 v124, v0
	v_mov_b32_e32 v125, v0
	v_mov_b32_e32 v126, v0
	v_mov_b32_e32 v127, v0
	.p2align	6

.LBB0_731:
	s_ashr_i32 s0, s36, 4
	s_ashr_i32 s6, s36, 7
	s_and_b32 s10, s0, 7
	s_mul_hi_i32 s1, s0, 0x88000
	s_mul_i32 s0, s0, 0x88000
	s_add_u32 s4, s37, s0
	s_addc_u32 s5, s38, s1
	s_ashr_i32 s7, s6, 31
	s_lshl_b64 s[8:9], s[6:7], 12
	s_lshl_b32 s7, s36, 8
	s_and_b32 s7, s7, 0xf00
	v_add_u32_e32 v96, s7, v137
	v_lshl_add_u64 v[0:1], s[8:9], 0, v[96:97]
	v_lshlrev_b64 v[2:3], 10, v[0:1]
	v_lshlrev_b64 v[0:1], 9, v[0:1]
	s_lshl_b32 s24, s10, 6
	v_lshl_add_u64 v[0:1], s[54:55], 0, v[0:1]
	v_lshl_add_u64 v[0:1], v[0:1], 0, s[24:25]
	v_lshl_add_u64 v[2:3], s[22:23], 0, v[2:3]
	s_lshl_b32 s8, s10, 7
	s_mov_b32 s9, s25
	v_lshl_add_u64 v[0:1], v[0:1], 0, v[162:163]
	v_lshl_add_u64 v[166:167], v[2:3], 0, s[8:9]
	v_add_co_u32_e32 v0, vcc, 0x4400000, v0
	v_lshl_add_u64 v[2:3], v[166:167], 0, v[162:163]
	s_nop 0
	v_addc_co_u32_e32 v1, vcc, 0, v1, vcc
	global_load_dwordx4 v[100:103], v[2:3], off
	global_load_dwordx4 v[104:107], v[2:3], off offset:32
	global_load_dwordx4 v[108:111], v[2:3], off offset:64
	global_load_dwordx4 v[112:115], v[2:3], off offset:96
	global_load_dwordx4 v[116:119], v[0:1], off
	global_load_dwordx4 v[120:123], v[0:1], off offset:32
	s_mul_i32 s34, s6, 0x44000
	s_mul_hi_i32 s35, s6, 0x44000
	s_add_u32 s6, s39, s34
	s_addc_u32 s7, s40, s35
	global_load_dwordx4 v[188:191], v154, s[4:5]
	s_add_u32 s12, s4, 0x2000
	s_addc_u32 s13, s5, 0
	global_load_dwordx4 v[128:131], v154, s[12:13]
	v_and_b32_e32 v196, 0xfff, v152
	global_load_dwordx4 v[124:127], v196, s[6:7]
	s_add_u32 s12, s6, 0x1000
	s_addc_u32 s13, s7, 0
	global_load_dwordx4 v[192:195], v196, s[12:13]
	v_lshl_add_u64 v[12:13], v[150:151], 0, s[0:1]
	global_load_dwordx4 v[4:7], v[12:13], off
	global_load_dwordx4 v[132:135], v[12:13], off offset:128
	v_add_u32_e32 v9, v143, v148
	v_add3_u32 v0, v177, v148, s41
	v_add_u32_e32 v1, v178, v148
	v_mov_b32_e32 v159, v97
	s_waitcnt vmcnt(0)
	ds_write_b128 v9, v[188:191]
	ds_write_b128 v186, v[124:127] offset:128
	ds_write2_b64 v0, v[4:5], v[6:7] offset1:1
	ds_write_b128 v1, v[128:131] offset:22016
	ds_write_b128 v186, v[192:195] offset:22144
	ds_write2_b64 v149, v[132:133], v[134:135] offset1:1
	s_waitcnt lgkmcnt(0)
	s_barrier
	ds_read_b128 v[0:3], v185
	ds_read_b128 v[4:7], v185 offset:32
	s_waitcnt lgkmcnt(1)
	v_mfma_f32_32x32x16_bf16 v[48:63], v[0:3], v[100:103], 0
	s_mov_b32 s4, 0
	s_mov_b32 s5, s4
	s_mov_b32 s6, s4
	s_mov_b32 s7, s4
	s_mov_b32 s8, s4
	s_mov_b32 s9, s4
	s_mov_b32 s10, s4
	s_waitcnt lgkmcnt(0)
	v_mfma_f32_32x32x16_bf16 v[48:63], v[4:7], v[104:107], v[48:63]
	ds_read_b128 v[0:3], v185 offset:64
	ds_read_b128 v[4:7], v185 offset:96
	s_mov_b32 s11, s4
	s_mov_b32 s12, s4
	s_mov_b32 s13, s4
	s_mov_b32 s14, s4
	s_mov_b32 s15, s4
	s_mov_b32 s16, s4
	s_waitcnt lgkmcnt(1)
	v_mfma_f32_32x32x16_bf16 v[48:63], v[0:3], v[108:111], v[48:63]
	s_mov_b32 s17, s4
	s_mov_b32 s18, s4
	s_mov_b32 s19, s4
	s_waitcnt lgkmcnt(0)
	v_mfma_f32_32x32x16_bf16 v[48:63], v[4:7], v[112:115], v[48:63]
	ds_read_b128 v[0:3], v185 offset:128
	ds_read_b128 v[4:7], v185 offset:160
	s_waitcnt lgkmcnt(1)
	v_mfma_f32_32x32x16_bf16 v[48:63], v[0:3], v[116:119], v[48:63]
	s_waitcnt lgkmcnt(0)
	v_mfma_f32_32x32x16_bf16 v[48:63], v[4:7], v[120:123], v[48:63]
	ds_read_b128 v[0:3], v185 offset:6656
	ds_read_b128 v[4:7], v185 offset:6688
	s_waitcnt lgkmcnt(1)
	v_mfma_f32_32x32x16_bf16 v[32:47], v[0:3], v[100:103], 0
	s_waitcnt lgkmcnt(0)
	v_mfma_f32_32x32x16_bf16 v[32:47], v[4:7], v[104:107], v[32:47]
	ds_read_b128 v[0:3], v185 offset:6720
	ds_read_b128 v[4:7], v185 offset:6752
	ds_read_b128 v[16:19], v185 offset:6816
	s_waitcnt lgkmcnt(2)
	v_mfma_f32_32x32x16_bf16 v[32:47], v[0:3], v[108:111], v[32:47]
	ds_read_b128 v[0:3], v185 offset:6784
	s_waitcnt lgkmcnt(2)
	v_mfma_f32_32x32x16_bf16 v[32:47], v[4:7], v[112:115], v[32:47]
	s_waitcnt lgkmcnt(0)
	v_mfma_f32_32x32x16_bf16 v[32:47], v[0:3], v[116:119], v[32:47]
	v_mov_b64_e32 v[0:1], s[4:5]
	v_mov_b64_e32 v[2:3], s[6:7]
	v_mov_b64_e32 v[4:5], s[8:9]
	v_mov_b64_e32 v[6:7], s[10:11]
	v_mov_b64_e32 v[8:9], s[12:13]
	v_mov_b64_e32 v[10:11], s[14:15]
	v_mov_b64_e32 v[12:13], s[16:17]
	v_mfma_f32_32x32x16_bf16 v[32:47], v[16:19], v[120:123], v[32:47]
	v_mov_b64_e32 v[14:15], s[18:19]
	s_nop 15
	s_nop 15
	s_nop 15
	v_mov_b64_e32 v[30:31], v[14:15]
	v_lshl_add_u64 v[98:99], v[152:153], 0, s[34:35]
	v_lshl_add_u64 v[168:169], v[146:147], 0, s[0:1]
	v_lshl_add_u64 v[170:171], v[154:155], 0, s[0:1]
	v_mov_b32_e32 v157, 0
	v_mov_b64_e32 v[28:29], v[12:13]
	v_mov_b64_e32 v[26:27], v[10:11]
	v_mov_b64_e32 v[24:25], v[8:9]
	v_mov_b64_e32 v[22:23], v[6:7]
	v_mov_b64_e32 v[20:21], v[4:5]
	v_mov_b64_e32 v[18:19], v[2:3]
	v_mov_b64_e32 v[16:17], v[0:1]
	v_mov_b32_e32 v96, 0
	v_mov_b32_e32 v228, 0x80000000
	v_mov_b32_e32 v229, v228
	v_mov_b32_e32 v230, v228
	v_mov_b32_e32 v231, v228
	v_mov_b32_e32 v232, v228
	v_mov_b32_e32 v233, v228
	v_mov_b32_e32 v234, v228
	v_mov_b32_e32 v235, v228
	v_mov_b32_e32 v236, v228
	v_mov_b32_e32 v237, v228
	v_mov_b32_e32 v238, v228
	v_mov_b32_e32 v239, v228
	v_mov_b32_e32 v240, v228
	v_mov_b32_e32 v241, v228
	v_mov_b32_e32 v242, v228
	v_mov_b32_e32 v243, v228
	s_add_u32 s48, s37, s0
	s_addc_u32 s49, s38, s1
	s_add_u32 s48, s48, 0x4000
	s_addc_u32 s49, s49, 0
	s_add_u32 s50, s39, s34
	s_addc_u32 s51, s40, s35
	s_add_u32 s50, s50, 0x2000
	s_addc_u32 s51, s51, 0
	s_add_u32 s60, s54, 0x1cd00000
	s_addc_u32 s61, s55, 0
	s_add_u32 s60, s60, s0
	s_addc_u32 s61, s61, s1
	s_add_u32 s60, s60, 0x100
	s_addc_u32 s61, s61, 0
	s_mov_b32 s44, 0
	s_movk_i32 s45, 0x5600
	s_mov_b32 s46, 0xac00
	v_add_u32_e32 v168, v141, v148
	v_add_u32_e32 v169, v174, v175
	v_add3_u32 v170, v176, v148, s41
	v_add3_u32 v171, v182, v136, s41
	v_add3_u32 v172, v183, v136, s41
	v_add_u32_e32 v173, v180, v179
	v_add_u32_e32 v98, v181, v179
	v_and_b32_e32 v99, 0xfff, v152
	v_mov_b32_e32 v212, 0
	v_mov_b32_e32 v213, 0
	v_mov_b32_e32 v214, 0
	v_mov_b32_e32 v215, 0
	v_mov_b32_e32 v216, 0
	v_mov_b32_e32 v217, 0
	v_mov_b32_e32 v218, 0
	v_mov_b32_e32 v219, 0
	v_mov_b32_e32 v220, 0
	v_mov_b32_e32 v221, 0
	v_mov_b32_e32 v222, 0
	v_mov_b32_e32 v223, 0
	global_load_dwordx4 v[128:131], v154, s[48:49]
	global_load_dwordx4 v[124:127], v99, s[50:51]
	global_load_dwordx4 v[132:135], v146, s[60:61]
	.p2align	6

.LBB0_848:
	s_ashr_i32 s23, s22, 31
	s_lshl_b64 s[8:9], s[22:23], 18
	s_add_u32 s24, s29, s8
	s_addc_u32 s25, s30, s9
	s_and_b64 s[8:9], s[2:3], exec
	s_cselect_b32 s23, s25, s5
	s_cselect_b32 s44, s24, s4
	s_ashr_i32 s21, s20, 31
	s_lshl_b64 s[8:9], s[20:21], 18
	s_add_u32 s26, s31, s8
	s_addc_u32 s27, s34, s9
	s_and_b64 s[8:9], s[2:3], exec
	s_cselect_b32 s21, s27, s7
	s_cselect_b32 s45, s26, s6
	s_add_u32 s4, s4, 0x20080
	s_addc_u32 s5, s5, 0
	s_add_u32 s50, s6, 0x100
	v_mov_b32_e32 v0, 0
	s_addc_u32 s51, s7, 0
	s_mov_b32 s60, -2
	v_mov_b32_e32 v1, v0
	v_mov_b32_e32 v2, v0
	v_mov_b32_e32 v3, v0
	v_mov_b32_e32 v4, v0
	v_mov_b32_e32 v5, v0
	v_mov_b32_e32 v6, v0
	v_mov_b32_e32 v7, v0
	v_mov_b32_e32 v16, v0
	v_mov_b32_e32 v17, v0
	v_mov_b32_e32 v18, v0
	v_mov_b32_e32 v19, v0
	v_mov_b32_e32 v20, v0
	v_mov_b32_e32 v21, v0
	v_mov_b32_e32 v22, v0
	v_mov_b32_e32 v23, v0
	v_mov_b32_e32 v32, v0
	v_mov_b32_e32 v33, v0
	v_mov_b32_e32 v34, v0
	v_mov_b32_e32 v35, v0
	v_mov_b32_e32 v36, v0
	v_mov_b32_e32 v37, v0
	v_mov_b32_e32 v38, v0
	v_mov_b32_e32 v39, v0
	v_mov_b32_e32 v48, v0
	v_mov_b32_e32 v49, v0
	v_mov_b32_e32 v50, v0
	v_mov_b32_e32 v51, v0
	v_mov_b32_e32 v52, v0
	v_mov_b32_e32 v53, v0
	v_mov_b32_e32 v54, v0
	v_mov_b32_e32 v55, v0
	v_mov_b32_e32 v8, v0
	v_mov_b32_e32 v9, v0
	v_mov_b32_e32 v10, v0
	v_mov_b32_e32 v11, v0
	v_mov_b32_e32 v12, v0
	v_mov_b32_e32 v13, v0
	v_mov_b32_e32 v14, v0
	v_mov_b32_e32 v15, v0
	v_mov_b32_e32 v24, v0
	v_mov_b32_e32 v25, v0
	v_mov_b32_e32 v26, v0
	v_mov_b32_e32 v27, v0
	v_mov_b32_e32 v28, v0
	v_mov_b32_e32 v29, v0
	v_mov_b32_e32 v30, v0
	v_mov_b32_e32 v31, v0
	v_mov_b32_e32 v40, v0
	v_mov_b32_e32 v41, v0
	v_mov_b32_e32 v42, v0
	v_mov_b32_e32 v43, v0
	v_mov_b32_e32 v44, v0
	v_mov_b32_e32 v45, v0
	v_mov_b32_e32 v46, v0
	v_mov_b32_e32 v47, v0
	v_mov_b32_e32 v56, v0
	v_mov_b32_e32 v57, v0
	v_mov_b32_e32 v58, v0
	v_mov_b32_e32 v59, v0
	v_mov_b32_e32 v60, v0
	v_mov_b32_e32 v61, v0
	v_mov_b32_e32 v62, v0
	v_mov_b32_e32 v63, v0
	v_mov_b32_e32 v64, v0
	v_mov_b32_e32 v65, v0
	v_mov_b32_e32 v66, v0
	v_mov_b32_e32 v67, v0
	v_mov_b32_e32 v68, v0
	v_mov_b32_e32 v69, v0
	v_mov_b32_e32 v70, v0
	v_mov_b32_e32 v71, v0
	v_mov_b32_e32 v80, v0
	v_mov_b32_e32 v81, v0
	v_mov_b32_e32 v82, v0
	v_mov_b32_e32 v83, v0
	v_mov_b32_e32 v84, v0
	v_mov_b32_e32 v85, v0
	v_mov_b32_e32 v86, v0
	v_mov_b32_e32 v87, v0
	v_mov_b32_e32 v96, v0
	v_mov_b32_e32 v97, v0
	v_mov_b32_e32 v98, v0
	v_mov_b32_e32 v99, v0
	v_mov_b32_e32 v100, v0
	v_mov_b32_e32 v101, v0
	v_mov_b32_e32 v102, v0
	v_mov_b32_e32 v103, v0
	v_mov_b32_e32 v112, v0
	v_mov_b32_e32 v113, v0
	v_mov_b32_e32 v114, v0
	v_mov_b32_e32 v115, v0
	v_mov_b32_e32 v116, v0
	v_mov_b32_e32 v117, v0
	v_mov_b32_e32 v118, v0
	v_mov_b32_e32 v119, v0
	v_mov_b32_e32 v72, v0
	v_mov_b32_e32 v73, v0
	v_mov_b32_e32 v74, v0
	v_mov_b32_e32 v75, v0
	v_mov_b32_e32 v76, v0
	v_mov_b32_e32 v77, v0
	v_mov_b32_e32 v78, v0
	v_mov_b32_e32 v79, v0
	v_mov_b32_e32 v88, v0
	v_mov_b32_e32 v89, v0
	v_mov_b32_e32 v90, v0
	v_mov_b32_e32 v91, v0
	v_mov_b32_e32 v92, v0
	v_mov_b32_e32 v93, v0
	v_mov_b32_e32 v94, v0
	v_mov_b32_e32 v95, v0
	v_mov_b32_e32 v104, v0
	v_mov_b32_e32 v105, v0
	v_mov_b32_e32 v106, v0
	v_mov_b32_e32 v107, v0
	v_mov_b32_e32 v108, v0
	v_mov_b32_e32 v109, v0
	v_mov_b32_e32 v110, v0
	v_mov_b32_e32 v111, v0
	v_mov_b32_e32 v120, v0
	v_mov_b32_e32 v121, v0
	v_mov_b32_e32 v122, v0
	v_mov_b32_e32 v123, v0
	s_waitcnt vmcnt(0)
	v_mov_b32_e32 v124, v0
	v_mov_b32_e32 v125, v0
	v_mov_b32_e32 v126, v0
	v_mov_b32_e32 v127, v0
	.p2align	6

.LBB0_927:
	s_ashr_i32 s23, s22, 31
	s_lshl_b64 s[24:25], s[22:23], 18
	s_add_u32 s24, s31, s24
	s_addc_u32 s25, s34, s25
	s_and_b64 s[26:27], s[2:3], exec
	s_cselect_b32 s23, s25, s5
	s_cselect_b32 s44, s24, s4
	s_ashr_i32 s21, s20, 31
	s_lshl_b64 s[26:27], s[20:21], 18
	s_add_u32 s26, s35, s26
	s_addc_u32 s27, s36, s27
	s_and_b64 s[28:29], s[2:3], exec
	s_cselect_b32 s21, s27, s7
	s_cselect_b32 s45, s26, s6
	s_add_u32 s4, s4, 0x20080
	s_addc_u32 s5, s5, 0
	s_add_u32 s60, s6, 0x100
	v_mov_b32_e32 v0, 0
	s_addc_u32 s61, s7, 0
	s_mov_b32 s66, -2
	v_mov_b32_e32 v1, v0
	v_mov_b32_e32 v2, v0
	v_mov_b32_e32 v3, v0
	v_mov_b32_e32 v4, v0
	v_mov_b32_e32 v5, v0
	v_mov_b32_e32 v6, v0
	v_mov_b32_e32 v7, v0
	v_mov_b32_e32 v16, v0
	v_mov_b32_e32 v17, v0
	v_mov_b32_e32 v18, v0
	v_mov_b32_e32 v19, v0
	v_mov_b32_e32 v20, v0
	v_mov_b32_e32 v21, v0
	v_mov_b32_e32 v22, v0
	v_mov_b32_e32 v23, v0
	v_mov_b32_e32 v32, v0
	v_mov_b32_e32 v33, v0
	v_mov_b32_e32 v34, v0
	v_mov_b32_e32 v35, v0
	v_mov_b32_e32 v36, v0
	v_mov_b32_e32 v37, v0
	v_mov_b32_e32 v38, v0
	v_mov_b32_e32 v39, v0
	v_mov_b32_e32 v48, v0
	v_mov_b32_e32 v49, v0
	v_mov_b32_e32 v50, v0
	v_mov_b32_e32 v51, v0
	v_mov_b32_e32 v52, v0
	v_mov_b32_e32 v53, v0
	v_mov_b32_e32 v54, v0
	v_mov_b32_e32 v55, v0
	v_mov_b32_e32 v8, v0
	v_mov_b32_e32 v9, v0
	v_mov_b32_e32 v10, v0
	v_mov_b32_e32 v11, v0
	v_mov_b32_e32 v12, v0
	v_mov_b32_e32 v13, v0
	v_mov_b32_e32 v14, v0
	v_mov_b32_e32 v15, v0
	v_mov_b32_e32 v24, v0
	v_mov_b32_e32 v25, v0
	v_mov_b32_e32 v26, v0
	v_mov_b32_e32 v27, v0
	v_mov_b32_e32 v28, v0
	v_mov_b32_e32 v29, v0
	v_mov_b32_e32 v30, v0
	v_mov_b32_e32 v31, v0
	v_mov_b32_e32 v40, v0
	v_mov_b32_e32 v41, v0
	v_mov_b32_e32 v42, v0
	v_mov_b32_e32 v43, v0
	v_mov_b32_e32 v44, v0
	v_mov_b32_e32 v45, v0
	v_mov_b32_e32 v46, v0
	v_mov_b32_e32 v47, v0
	v_mov_b32_e32 v56, v0
	v_mov_b32_e32 v57, v0
	v_mov_b32_e32 v58, v0
	v_mov_b32_e32 v59, v0
	v_mov_b32_e32 v60, v0
	v_mov_b32_e32 v61, v0
	v_mov_b32_e32 v62, v0
	v_mov_b32_e32 v63, v0
	v_mov_b32_e32 v64, v0
	v_mov_b32_e32 v65, v0
	v_mov_b32_e32 v66, v0
	v_mov_b32_e32 v67, v0
	v_mov_b32_e32 v68, v0
	v_mov_b32_e32 v69, v0
	v_mov_b32_e32 v70, v0
	v_mov_b32_e32 v71, v0
	v_mov_b32_e32 v80, v0
	v_mov_b32_e32 v81, v0
	v_mov_b32_e32 v82, v0
	v_mov_b32_e32 v83, v0
	v_mov_b32_e32 v84, v0
	v_mov_b32_e32 v85, v0
	v_mov_b32_e32 v86, v0
	v_mov_b32_e32 v87, v0
	v_mov_b32_e32 v96, v0
	v_mov_b32_e32 v97, v0
	v_mov_b32_e32 v98, v0
	v_mov_b32_e32 v99, v0
	v_mov_b32_e32 v100, v0
	v_mov_b32_e32 v101, v0
	v_mov_b32_e32 v102, v0
	v_mov_b32_e32 v103, v0
	v_mov_b32_e32 v112, v0
	v_mov_b32_e32 v113, v0
	v_mov_b32_e32 v114, v0
	v_mov_b32_e32 v115, v0
	v_mov_b32_e32 v116, v0
	v_mov_b32_e32 v117, v0
	v_mov_b32_e32 v118, v0
	v_mov_b32_e32 v119, v0
	v_mov_b32_e32 v72, v0
	v_mov_b32_e32 v73, v0
	v_mov_b32_e32 v74, v0
	v_mov_b32_e32 v75, v0
	v_mov_b32_e32 v76, v0
	v_mov_b32_e32 v77, v0
	v_mov_b32_e32 v78, v0
	v_mov_b32_e32 v79, v0
	v_mov_b32_e32 v88, v0
	v_mov_b32_e32 v89, v0
	v_mov_b32_e32 v90, v0
	v_mov_b32_e32 v91, v0
	v_mov_b32_e32 v92, v0
	v_mov_b32_e32 v93, v0
	v_mov_b32_e32 v94, v0
	v_mov_b32_e32 v95, v0
	v_mov_b32_e32 v104, v0
	v_mov_b32_e32 v105, v0
	v_mov_b32_e32 v106, v0
	v_mov_b32_e32 v107, v0
	v_mov_b32_e32 v108, v0
	v_mov_b32_e32 v109, v0
	v_mov_b32_e32 v110, v0
	v_mov_b32_e32 v111, v0
	v_mov_b32_e32 v120, v0
	v_mov_b32_e32 v121, v0
	v_mov_b32_e32 v122, v0
	v_mov_b32_e32 v123, v0
	s_waitcnt vmcnt(0)
	v_mov_b32_e32 v124, v0
	v_mov_b32_e32 v125, v0
	v_mov_b32_e32 v126, v0
	v_mov_b32_e32 v127, v0
	.p2align	6

.LBB0_1008:
	s_ashr_i32 s19, s18, 31
	s_lshl_b64 s[20:21], s[18:19], 19
	s_add_u32 s20, s36, s20
	s_addc_u32 s21, s37, s21
	s_and_b64 s[22:23], s[4:5], exec
	s_cselect_b32 s19, s21, s29
	s_cselect_b32 s25, s20, s28
	s_ashr_i32 s17, s16, 31
	s_lshl_b64 s[22:23], s[16:17], 19
	s_add_u32 s22, s38, s22
	s_addc_u32 s23, s39, s23
	s_and_b64 s[34:35], s[4:5], exec
	s_cselect_b32 s17, s23, s31
	s_cselect_b32 s27, s22, s30
	s_add_u32 s28, s28, 0x40080
	s_addc_u32 s29, s29, 0
	s_add_u32 s60, s30, 0x100
	v_mov_b32_e32 v0, 0
	s_addc_u32 s61, s31, 0
	s_mov_b32 s67, -2
	s_waitcnt lgkmcnt(0)
	v_mov_b32_e32 v1, v0
	v_mov_b32_e32 v2, v0
	v_mov_b32_e32 v3, v0
	v_mov_b32_e32 v4, v0
	v_mov_b32_e32 v5, v0
	v_mov_b32_e32 v6, v0
	v_mov_b32_e32 v7, v0
	v_mov_b32_e32 v16, v0
	v_mov_b32_e32 v17, v0
	v_mov_b32_e32 v18, v0
	v_mov_b32_e32 v19, v0
	v_mov_b32_e32 v20, v0
	v_mov_b32_e32 v21, v0
	v_mov_b32_e32 v22, v0
	v_mov_b32_e32 v23, v0
	v_mov_b32_e32 v32, v0
	v_mov_b32_e32 v33, v0
	v_mov_b32_e32 v34, v0
	v_mov_b32_e32 v35, v0
	v_mov_b32_e32 v36, v0
	v_mov_b32_e32 v37, v0
	v_mov_b32_e32 v38, v0
	v_mov_b32_e32 v39, v0
	v_mov_b32_e32 v48, v0
	v_mov_b32_e32 v49, v0
	v_mov_b32_e32 v50, v0
	v_mov_b32_e32 v51, v0
	v_mov_b32_e32 v52, v0
	v_mov_b32_e32 v53, v0
	v_mov_b32_e32 v54, v0
	v_mov_b32_e32 v55, v0
	v_mov_b32_e32 v8, v0
	v_mov_b32_e32 v9, v0
	v_mov_b32_e32 v10, v0
	v_mov_b32_e32 v11, v0
	v_mov_b32_e32 v12, v0
	v_mov_b32_e32 v13, v0
	v_mov_b32_e32 v14, v0
	v_mov_b32_e32 v15, v0
	v_mov_b32_e32 v24, v0
	v_mov_b32_e32 v25, v0
	v_mov_b32_e32 v26, v0
	v_mov_b32_e32 v27, v0
	v_mov_b32_e32 v28, v0
	v_mov_b32_e32 v29, v0
	v_mov_b32_e32 v30, v0
	v_mov_b32_e32 v31, v0
	v_mov_b32_e32 v40, v0
	v_mov_b32_e32 v41, v0
	v_mov_b32_e32 v42, v0
	v_mov_b32_e32 v43, v0
	v_mov_b32_e32 v44, v0
	v_mov_b32_e32 v45, v0
	v_mov_b32_e32 v46, v0
	v_mov_b32_e32 v47, v0
	v_mov_b32_e32 v56, v0
	v_mov_b32_e32 v57, v0
	v_mov_b32_e32 v58, v0
	v_mov_b32_e32 v59, v0
	v_mov_b32_e32 v60, v0
	v_mov_b32_e32 v61, v0
	v_mov_b32_e32 v62, v0
	v_mov_b32_e32 v63, v0
	v_mov_b32_e32 v64, v0
	v_mov_b32_e32 v65, v0
	v_mov_b32_e32 v66, v0
	v_mov_b32_e32 v67, v0
	v_mov_b32_e32 v68, v0
	v_mov_b32_e32 v69, v0
	v_mov_b32_e32 v70, v0
	v_mov_b32_e32 v71, v0
	v_mov_b32_e32 v96, v0
	v_mov_b32_e32 v97, v0
	v_mov_b32_e32 v98, v0
	v_mov_b32_e32 v99, v0
	v_mov_b32_e32 v100, v0
	v_mov_b32_e32 v101, v0
	v_mov_b32_e32 v102, v0
	v_mov_b32_e32 v103, v0
	v_mov_b32_e32 v112, v0
	v_mov_b32_e32 v113, v0
	v_mov_b32_e32 v114, v0
	v_mov_b32_e32 v115, v0
	v_mov_b32_e32 v116, v0
	v_mov_b32_e32 v117, v0
	v_mov_b32_e32 v118, v0
	v_mov_b32_e32 v119, v0
	s_waitcnt vmcnt(0)
	v_mov_b32_e32 v128, v0
	v_mov_b32_e32 v129, v0
	v_mov_b32_e32 v130, v0
	v_mov_b32_e32 v131, v0
	v_mov_b32_e32 v132, v0
	v_mov_b32_e32 v133, v0
	v_mov_b32_e32 v134, v0
	v_mov_b32_e32 v135, v0
	v_mov_b32_e32 v72, v0
	v_mov_b32_e32 v73, v0
	v_mov_b32_e32 v74, v0
	v_mov_b32_e32 v75, v0
	v_mov_b32_e32 v76, v0
	v_mov_b32_e32 v77, v0
	v_mov_b32_e32 v78, v0
	v_mov_b32_e32 v79, v0
	v_mov_b32_e32 v104, v0
	v_mov_b32_e32 v105, v0
	v_mov_b32_e32 v106, v0
	v_mov_b32_e32 v107, v0
	v_mov_b32_e32 v108, v0
	v_mov_b32_e32 v109, v0
	v_mov_b32_e32 v110, v0
	v_mov_b32_e32 v111, v0
	v_mov_b32_e32 v120, v0
	v_mov_b32_e32 v121, v0
	v_mov_b32_e32 v122, v0
	v_mov_b32_e32 v123, v0
	v_mov_b32_e32 v124, v0
	v_mov_b32_e32 v125, v0
	v_mov_b32_e32 v126, v0
	v_mov_b32_e32 v127, v0
	v_mov_b32_e32 v136, v0
	v_mov_b32_e32 v137, v0
	v_mov_b32_e32 v138, v0
	v_mov_b32_e32 v139, v0
	v_mov_b32_e32 v140, v0
	v_mov_b32_e32 v141, v0
	v_mov_b32_e32 v142, v0
	v_mov_b32_e32 v143, v0
	.p2align	6

.LBB0_1095:
	s_ashr_i32 s19, s18, 31
	s_lshl_b64 s[20:21], s[18:19], 19
	s_add_u32 s20, s30, s20
	s_addc_u32 s21, s31, s21
	s_and_b64 s[22:23], s[2:3], exec
	s_cselect_b32 s19, s21, s25
	s_cselect_b32 s61, s20, s24
	s_ashr_i32 s17, s16, 31
	s_lshl_b64 s[22:23], s[16:17], 19
	s_add_u32 s22, s34, s22
	s_addc_u32 s23, s35, s23
	s_and_b64 s[28:29], s[2:3], exec
	s_cselect_b32 s17, s23, s27
	s_cselect_b32 s66, s22, s26
	s_add_u32 s24, s24, 0x40080
	s_addc_u32 s25, s25, 0
	s_add_u32 s67, s26, 0x100
	v_mov_b32_e32 v0, 0
	s_addc_u32 s68, s27, 0
	s_mov_b32 s69, -2
	v_mov_b32_e32 v1, v0
	v_mov_b32_e32 v2, v0
	v_mov_b32_e32 v3, v0
	v_mov_b32_e32 v4, v0
	v_mov_b32_e32 v5, v0
	v_mov_b32_e32 v6, v0
	v_mov_b32_e32 v7, v0
	v_mov_b32_e32 v16, v0
	v_mov_b32_e32 v17, v0
	v_mov_b32_e32 v18, v0
	v_mov_b32_e32 v19, v0
	v_mov_b32_e32 v20, v0
	v_mov_b32_e32 v21, v0
	v_mov_b32_e32 v22, v0
	v_mov_b32_e32 v23, v0
	v_mov_b32_e32 v32, v0
	v_mov_b32_e32 v33, v0
	v_mov_b32_e32 v34, v0
	v_mov_b32_e32 v35, v0
	v_mov_b32_e32 v36, v0
	v_mov_b32_e32 v37, v0
	v_mov_b32_e32 v38, v0
	v_mov_b32_e32 v39, v0
	v_mov_b32_e32 v48, v0
	v_mov_b32_e32 v49, v0
	v_mov_b32_e32 v50, v0
	v_mov_b32_e32 v51, v0
	v_mov_b32_e32 v52, v0
	v_mov_b32_e32 v53, v0
	v_mov_b32_e32 v54, v0
	v_mov_b32_e32 v55, v0
	v_mov_b32_e32 v8, v0
	v_mov_b32_e32 v9, v0
	v_mov_b32_e32 v10, v0
	v_mov_b32_e32 v11, v0
	v_mov_b32_e32 v12, v0
	v_mov_b32_e32 v13, v0
	v_mov_b32_e32 v14, v0
	v_mov_b32_e32 v15, v0
	v_mov_b32_e32 v24, v0
	v_mov_b32_e32 v25, v0
	v_mov_b32_e32 v26, v0
	v_mov_b32_e32 v27, v0
	v_mov_b32_e32 v28, v0
	v_mov_b32_e32 v29, v0
	v_mov_b32_e32 v30, v0
	v_mov_b32_e32 v31, v0
	v_mov_b32_e32 v40, v0
	v_mov_b32_e32 v41, v0
	v_mov_b32_e32 v42, v0
	v_mov_b32_e32 v43, v0
	v_mov_b32_e32 v44, v0
	v_mov_b32_e32 v45, v0
	v_mov_b32_e32 v46, v0
	v_mov_b32_e32 v47, v0
	v_mov_b32_e32 v56, v0
	v_mov_b32_e32 v57, v0
	v_mov_b32_e32 v58, v0
	v_mov_b32_e32 v59, v0
	v_mov_b32_e32 v60, v0
	v_mov_b32_e32 v61, v0
	v_mov_b32_e32 v62, v0
	v_mov_b32_e32 v63, v0
	v_mov_b32_e32 v64, v0
	v_mov_b32_e32 v65, v0
	v_mov_b32_e32 v66, v0
	v_mov_b32_e32 v67, v0
	v_mov_b32_e32 v68, v0
	v_mov_b32_e32 v69, v0
	v_mov_b32_e32 v70, v0
	v_mov_b32_e32 v71, v0
	v_mov_b32_e32 v80, v0
	v_mov_b32_e32 v81, v0
	v_mov_b32_e32 v82, v0
	v_mov_b32_e32 v83, v0
	v_mov_b32_e32 v84, v0
	v_mov_b32_e32 v85, v0
	v_mov_b32_e32 v86, v0
	v_mov_b32_e32 v87, v0
	v_mov_b32_e32 v96, v0
	v_mov_b32_e32 v97, v0
	v_mov_b32_e32 v98, v0
	v_mov_b32_e32 v99, v0
	v_mov_b32_e32 v100, v0
	v_mov_b32_e32 v101, v0
	v_mov_b32_e32 v102, v0
	v_mov_b32_e32 v103, v0
	v_mov_b32_e32 v112, v0
	v_mov_b32_e32 v113, v0
	v_mov_b32_e32 v114, v0
	v_mov_b32_e32 v115, v0
	v_mov_b32_e32 v116, v0
	v_mov_b32_e32 v117, v0
	v_mov_b32_e32 v118, v0
	v_mov_b32_e32 v119, v0
	v_mov_b32_e32 v72, v0
	v_mov_b32_e32 v73, v0
	v_mov_b32_e32 v74, v0
	v_mov_b32_e32 v75, v0
	v_mov_b32_e32 v76, v0
	v_mov_b32_e32 v77, v0
	v_mov_b32_e32 v78, v0
	v_mov_b32_e32 v79, v0
	v_mov_b32_e32 v88, v0
	v_mov_b32_e32 v89, v0
	v_mov_b32_e32 v90, v0
	v_mov_b32_e32 v91, v0
	v_mov_b32_e32 v92, v0
	v_mov_b32_e32 v93, v0
	v_mov_b32_e32 v94, v0
	v_mov_b32_e32 v95, v0
	v_mov_b32_e32 v104, v0
	v_mov_b32_e32 v105, v0
	v_mov_b32_e32 v106, v0
	v_mov_b32_e32 v107, v0
	v_mov_b32_e32 v108, v0
	v_mov_b32_e32 v109, v0
	v_mov_b32_e32 v110, v0
	v_mov_b32_e32 v111, v0
	v_mov_b32_e32 v120, v0
	v_mov_b32_e32 v121, v0
	v_mov_b32_e32 v122, v0
	v_mov_b32_e32 v123, v0
	s_waitcnt vmcnt(0)
	v_mov_b32_e32 v124, v0
	v_mov_b32_e32 v125, v0
	v_mov_b32_e32 v126, v0
	v_mov_b32_e32 v127, v0
	.p2align	6

.LBB0_1273:
	s_add_u32 s16, s16, 0x160080
	s_addc_u32 s17, s17, 0
	s_add_u32 s48, s18, 0x100
	v_mov_b32_e32 v0, 0
	s_addc_u32 s49, s19, 0
	s_mov_b32 s50, -2
	v_mov_b32_e32 v1, v0
	v_mov_b32_e32 v2, v0
	v_mov_b32_e32 v3, v0
	v_mov_b32_e32 v4, v0
	v_mov_b32_e32 v5, v0
	v_mov_b32_e32 v6, v0
	v_mov_b32_e32 v7, v0
	v_mov_b32_e32 v16, v0
	v_mov_b32_e32 v17, v0
	v_mov_b32_e32 v18, v0
	v_mov_b32_e32 v19, v0
	v_mov_b32_e32 v20, v0
	v_mov_b32_e32 v21, v0
	v_mov_b32_e32 v22, v0
	v_mov_b32_e32 v23, v0
	v_mov_b32_e32 v32, v0
	v_mov_b32_e32 v33, v0
	v_mov_b32_e32 v34, v0
	v_mov_b32_e32 v35, v0
	v_mov_b32_e32 v36, v0
	v_mov_b32_e32 v37, v0
	v_mov_b32_e32 v38, v0
	v_mov_b32_e32 v39, v0
	v_mov_b32_e32 v48, v0
	v_mov_b32_e32 v49, v0
	v_mov_b32_e32 v50, v0
	v_mov_b32_e32 v51, v0
	v_mov_b32_e32 v52, v0
	v_mov_b32_e32 v53, v0
	v_mov_b32_e32 v54, v0
	v_mov_b32_e32 v55, v0
	v_mov_b32_e32 v8, v0
	v_mov_b32_e32 v9, v0
	v_mov_b32_e32 v10, v0
	v_mov_b32_e32 v11, v0
	v_mov_b32_e32 v12, v0
	v_mov_b32_e32 v13, v0
	v_mov_b32_e32 v14, v0
	v_mov_b32_e32 v15, v0
	v_mov_b32_e32 v24, v0
	v_mov_b32_e32 v25, v0
	v_mov_b32_e32 v26, v0
	v_mov_b32_e32 v27, v0
	v_mov_b32_e32 v28, v0
	v_mov_b32_e32 v29, v0
	v_mov_b32_e32 v30, v0
	v_mov_b32_e32 v31, v0
	v_mov_b32_e32 v40, v0
	v_mov_b32_e32 v41, v0
	v_mov_b32_e32 v42, v0
	v_mov_b32_e32 v43, v0
	v_mov_b32_e32 v44, v0
	v_mov_b32_e32 v45, v0
	v_mov_b32_e32 v46, v0
	v_mov_b32_e32 v47, v0
	v_mov_b32_e32 v56, v0
	v_mov_b32_e32 v57, v0
	v_mov_b32_e32 v58, v0
	v_mov_b32_e32 v59, v0
	v_mov_b32_e32 v60, v0
	v_mov_b32_e32 v61, v0
	v_mov_b32_e32 v62, v0
	v_mov_b32_e32 v63, v0
	v_mov_b32_e32 v64, v0
	v_mov_b32_e32 v65, v0
	v_mov_b32_e32 v66, v0
	v_mov_b32_e32 v67, v0
	v_mov_b32_e32 v68, v0
	v_mov_b32_e32 v69, v0
	v_mov_b32_e32 v70, v0
	v_mov_b32_e32 v71, v0
	v_mov_b32_e32 v80, v0
	v_mov_b32_e32 v81, v0
	v_mov_b32_e32 v82, v0
	v_mov_b32_e32 v83, v0
	v_mov_b32_e32 v84, v0
	v_mov_b32_e32 v85, v0
	v_mov_b32_e32 v86, v0
	v_mov_b32_e32 v87, v0
	v_mov_b32_e32 v96, v0
	v_mov_b32_e32 v97, v0
	v_mov_b32_e32 v98, v0
	v_mov_b32_e32 v99, v0
	v_mov_b32_e32 v100, v0
	v_mov_b32_e32 v101, v0
	v_mov_b32_e32 v102, v0
	v_mov_b32_e32 v103, v0
	v_mov_b32_e32 v112, v0
	v_mov_b32_e32 v113, v0
	v_mov_b32_e32 v114, v0
	v_mov_b32_e32 v115, v0
	v_mov_b32_e32 v116, v0
	v_mov_b32_e32 v117, v0
	v_mov_b32_e32 v118, v0
	v_mov_b32_e32 v119, v0
	v_mov_b32_e32 v72, v0
	v_mov_b32_e32 v73, v0
	v_mov_b32_e32 v74, v0
	v_mov_b32_e32 v75, v0
	v_mov_b32_e32 v76, v0
	v_mov_b32_e32 v77, v0
	v_mov_b32_e32 v78, v0
	v_mov_b32_e32 v79, v0
	v_mov_b32_e32 v88, v0
	v_mov_b32_e32 v89, v0
	v_mov_b32_e32 v90, v0
	v_mov_b32_e32 v91, v0
	v_mov_b32_e32 v92, v0
	v_mov_b32_e32 v93, v0
	v_mov_b32_e32 v94, v0
	v_mov_b32_e32 v95, v0
	v_mov_b32_e32 v104, v0
	v_mov_b32_e32 v105, v0
	v_mov_b32_e32 v106, v0
	v_mov_b32_e32 v107, v0
	v_mov_b32_e32 v108, v0
	v_mov_b32_e32 v109, v0
	v_mov_b32_e32 v110, v0
	v_mov_b32_e32 v111, v0
	v_mov_b32_e32 v120, v0
	v_mov_b32_e32 v121, v0
	v_mov_b32_e32 v122, v0
	v_mov_b32_e32 v123, v0
	v_mov_b32_e32 v124, v0
	v_mov_b32_e32 v125, v0
	v_mov_b32_e32 v126, v0
	v_mov_b32_e32 v127, v0
	.p2align	6
